# mix row loop: all eight row loads issued before the first wait
# baseline (speedup 1.0000x reference)
.LBB0_135:
	v_add_u32_e32 v30, v80, v83
	v_ashrrev_i32_e32 v31, 31, v30
	v_lshlrev_b64 v[0:1], 13, v[30:31]
	v_lshl_add_u64 v[0:1], v[26:27], 0, v[0:1]
	global_load_dwordx4 v[16:19], v[0:1], off
	global_load_dwordx4 v[8:11], v[0:1], off offset:1024
	global_load_dwordx4 v[32:35], v[0:1], off offset:2048
	global_load_dwordx4 v[36:39], v[0:1], off offset:3072
	v_add_co_u32_e32 v40, vcc, s1, v0
	s_nop 1
	v_addc_co_u32_e32 v41, vcc, 0, v1, vcc
	global_load_dwordx4 v[20:23], v[40:41], off
	global_load_dwordx4 v[12:15], v[40:41], off offset:1024
	global_load_dwordx4 v[0:3], v[40:41], off offset:3072
	global_load_dwordx4 v[4:7], v[40:41], off offset:2048
	s_waitcnt vmcnt(7)
	v_mov_b32_e32 v110, v17
	s_waitcnt vmcnt(6)
	v_mov_b32_e32 v111, v9
	v_mov_b32_e32 v114, v19
	v_mov_b32_e32 v115, v11
	v_mov_b32_e32 v40, v16
	v_mov_b32_e32 v41, v8
	v_mov_b32_e32 v112, v18
	v_mov_b32_e32 v113, v10
	s_waitcnt vmcnt(5)
	v_pk_mul_f32 v[116:117], v[34:35], v[34:35]
	v_pk_mul_f32 v[118:119], v[32:33], v[32:33]
	v_pk_mul_f32 v[110:111], v[110:111], v[110:111]
	v_pk_mul_f32 v[114:115], v[114:115], v[114:115]
	v_pk_mov_b32 v[124:125], v[118:119], v[116:117] op_sel:[1,0]
	v_mov_b32_e32 v119, v117
	v_pk_fma_f32 v[40:41], v[40:41], v[40:41], v[110:111]
	v_pk_fma_f32 v[110:111], v[112:113], v[112:113], v[114:115]
	s_waitcnt vmcnt(4)
	v_mul_f32_e32 v120, v37, v37
	v_mul_f32_e32 v122, v39, v39
	v_pk_add_f32 v[112:113], v[124:125], v[118:119]
	v_pk_add_f32 v[40:41], v[40:41], v[110:111]
	v_pk_fma_f32 v[116:117], v[36:37], v[36:37], v[120:121] op_sel_hi:[1,1,0]
	v_pk_fma_f32 v[120:121], v[38:39], v[38:39], v[122:123] op_sel_hi:[1,1,0]
	v_pk_add_f32 v[110:111], v[112:113], v[112:113] op_sel:[0,1] op_sel_hi:[1,0]
	v_pk_add_f32 v[40:41], v[40:41], v[40:41] op_sel:[0,1] op_sel_hi:[1,0]
	ds_read_b128 v[86:89], v77
	ds_read_b128 v[90:93], v77 offset:1024
	ds_read_b128 v[94:97], v82 offset:8192
	ds_read_b128 v[98:101], v82 offset:9216
	ds_read_b128 v[102:105], v82
	ds_read_b128 v[106:109], v82 offset:1024
	s_waitcnt lgkmcnt(3)
	v_pk_add_f32 v[94:95], v[94:95], 1.0 op_sel_hi:[1,0]
	s_waitcnt lgkmcnt(2)
	v_pk_add_f32 v[98:99], v[98:99], 1.0 op_sel_hi:[1,0]
	s_waitcnt vmcnt(3)
	v_mul_f32_e32 v129, v20, v20
	v_mul_f32_e32 v131, v21, v21
	v_mul_f32_e32 v132, v22, v22
	v_mul_f32_e32 v133, v23, v23
	s_waitcnt vmcnt(2)
	v_pk_mul_f32 v[122:123], v[14:15], v[14:15]
	v_pk_mul_f32 v[126:127], v[12:13], v[12:13]
	v_mov_b32_e32 v117, v132
	v_mov_b32_e32 v121, v133
	v_mov_b32_e32 v111, v131
	v_mov_b32_e32 v41, v129
	v_pk_mov_b32 v[114:115], v[126:127], v[122:123] op_sel:[1,0]
	v_mov_b32_e32 v127, v123
	v_pk_add_f32 v[112:113], v[116:117], v[120:121]
	v_pk_add_f32 v[40:41], v[40:41], v[110:111]
	s_waitcnt vmcnt(0)
	v_mul_f32_e32 v128, v5, v5
	v_mul_f32_e32 v130, v7, v7
	v_pk_add_f32 v[114:115], v[114:115], v[126:127]
	v_pk_add_f32 v[40:41], v[40:41], v[112:113]
	v_mul_f32_e32 v134, v0, v0
	v_mul_f32_e32 v135, v1, v1
	v_mul_f32_e32 v136, v2, v2
	v_mul_f32_e32 v137, v3, v3
	v_pk_fma_f32 v[118:119], v[4:5], v[4:5], v[128:129] op_sel_hi:[1,1,0]
	v_pk_fma_f32 v[122:123], v[6:7], v[6:7], v[130:131] op_sel_hi:[1,1,0]
	v_pk_add_f32 v[114:115], v[114:115], v[114:115] op_sel:[0,1] op_sel_hi:[1,0]
	v_pk_add_f32 v[40:41], v[40:41], v[40:41] op_sel:[0,1] op_sel_hi:[1,0]
	v_mov_b32_e32 v119, v136
	v_mov_b32_e32 v123, v137
	v_mov_b32_e32 v115, v135
	v_mov_b32_e32 v41, v134
	v_pk_add_f32 v[116:117], v[118:119], v[122:123]
	v_pk_add_f32 v[40:41], v[40:41], v[114:115]
	s_nop 0
	v_pk_add_f32 v[40:41], v[40:41], v[116:117]
	ds_read_b128 v[110:113], v77 offset:2048
	ds_read_b128 v[114:117], v77 offset:3072
	ds_read_b128 v[118:121], v82 offset:10240
	ds_read_b128 v[122:125], v82 offset:11264
	v_add_f32_e32 v40, v40, v41
	ds_read_b128 v[126:129], v82 offset:2048
	ds_read_b128 v[130:133], v82 offset:3072
	v_add_f32_dpp v40, v40, v40 quad_perm:[1,0,3,2] row_mask:0xf bank_mask:0xf bound_ctrl:1
	s_waitcnt lgkmcnt(3)
	v_pk_add_f32 v[118:119], v[118:119], 1.0 op_sel_hi:[1,0]
	v_add_f32_dpp v40, v40, v40 quad_perm:[2,3,0,1] row_mask:0xf bank_mask:0xf bound_ctrl:1
	s_nop 1
	v_add_f32_dpp v40, v40, v40 row_half_mirror row_mask:0xf bank_mask:0xf bound_ctrl:1
	s_nop 1
	v_add_f32_dpp v40, v40, v40 row_mirror row_mask:0xf bank_mask:0xf bound_ctrl:1
	ds_bpermute_b32 v41, v75, v40
	s_waitcnt lgkmcnt(0)
	v_add_f32_e32 v134, v40, v41
	ds_bpermute_b32 v135, v76, v134
	v_pk_add_f32 v[40:41], v[96:97], 1.0 op_sel_hi:[1,0]
	v_pk_add_f32 v[96:97], v[100:101], 1.0 op_sel_hi:[1,0]
	s_waitcnt lgkmcnt(0)
	v_add_f32_e32 v100, v134, v135
	v_fmamk_f32 v100, v100, 0x3a000000, v81
	v_mul_f32_e32 v101, 0x4b800000, v100
	v_cmp_gt_f32_e32 vcc, s3, v100
	s_nop 1
	v_cndmask_b32_e32 v100, v100, v101, vcc
	v_rsq_f32_e32 v134, v100
	v_pk_add_f32 v[100:101], v[120:121], 1.0 op_sel_hi:[1,0]
	v_mul_f32_e32 v120, 0x45800000, v134
	v_cndmask_b32_e32 v120, v134, v120, vcc
	v_pk_mul_f32 v[18:19], v[18:19], v[120:121] op_sel_hi:[1,0]
	v_pk_mul_f32 v[16:17], v[16:17], v[120:121] op_sel_hi:[1,0]
	v_pk_mul_f32 v[8:9], v[8:9], v[120:121] op_sel_hi:[1,0]
	v_pk_mul_f32 v[10:11], v[10:11], v[120:121] op_sel_hi:[1,0]
	v_pk_mul_f32 v[32:33], v[32:33], v[120:121] op_sel_hi:[1,0]
	v_pk_mul_f32 v[16:17], v[86:87], v[16:17]
	v_pk_mul_f32 v[18:19], v[88:89], v[18:19]
	v_pk_mul_f32 v[86:87], v[90:91], v[8:9]
	v_pk_mul_f32 v[38:39], v[38:39], v[120:121] op_sel_hi:[1,0]
	v_pk_mul_f32 v[36:37], v[36:37], v[120:121] op_sel_hi:[1,0]
	v_pk_mul_f32 v[34:35], v[34:35], v[120:121] op_sel_hi:[1,0]
	v_pk_mul_f32 v[88:89], v[92:93], v[10:11]
	v_pk_mul_f32 v[90:91], v[110:111], v[32:33]
	v_pk_fma_f32 v[8:9], v[40:41], v[18:19], v[104:105]
	v_pk_fma_f32 v[18:19], v[98:99], v[86:87], v[106:107]
	v_pk_mul_f32 v[40:41], v[114:115], v[36:37]
	v_pk_mul_f32 v[36:37], v[116:117], v[38:39]
	v_pk_add_f32 v[38:39], v[124:125], 1.0 op_sel_hi:[1,0]
	v_pk_add_f32 v[86:87], v[122:123], 1.0 op_sel_hi:[1,0]
	v_pk_mul_f32 v[32:33], v[112:113], v[34:35]
	v_pk_fma_f32 v[10:11], v[94:95], v[16:17], v[102:103]
	v_pk_fma_f32 v[16:17], v[96:97], v[88:89], v[108:109]
	v_pk_fma_f32 v[34:35], v[118:119], v[90:91], v[126:127]
	v_pk_fma_f32 v[36:37], v[38:39], v[36:37], v[132:133]
	v_pk_fma_f32 v[38:39], v[86:87], v[40:41], v[130:131]
	ds_read_b128 v[86:89], v77 offset:4096
	ds_read_b128 v[90:93], v82 offset:12288
	ds_read_b128 v[94:97], v82 offset:4096
	v_pk_mul_f32 v[22:23], v[22:23], v[120:121] op_sel_hi:[1,0]
	v_pk_mul_f32 v[20:21], v[20:21], v[120:121] op_sel_hi:[1,0]
	v_pk_fma_f32 v[32:33], v[100:101], v[32:33], v[128:129]
	ds_read_b128 v[98:101], v77 offset:5120
	s_waitcnt lgkmcnt(3)
	v_pk_mul_f32 v[40:41], v[86:87], v[20:21]
	v_pk_mul_f32 v[20:21], v[88:89], v[22:23]
	ds_read_b128 v[86:89], v82 offset:13312
	s_waitcnt lgkmcnt(3)
	v_pk_add_f32 v[22:23], v[92:93], 1.0 op_sel_hi:[1,0]
	v_pk_add_f32 v[102:103], v[90:91], 1.0 op_sel_hi:[1,0]
	ds_read_b128 v[90:93], v82 offset:5120
	v_pk_mul_f32 v[14:15], v[14:15], v[120:121] op_sel_hi:[1,0]
	v_pk_mul_f32 v[12:13], v[12:13], v[120:121] op_sel_hi:[1,0]
	s_waitcnt lgkmcnt(3)
	v_pk_fma_f32 v[20:21], v[22:23], v[20:21], v[96:97]
	v_pk_fma_f32 v[22:23], v[102:103], v[40:41], v[94:95]
	s_waitcnt lgkmcnt(2)
	v_pk_mul_f32 v[40:41], v[12:13], v[98:99]
	v_pk_mul_f32 v[12:13], v[14:15], v[100:101]
	s_waitcnt lgkmcnt(1)
	v_pk_add_f32 v[14:15], v[88:89], 1.0 op_sel_hi:[1,0]
	v_pk_add_f32 v[86:87], v[86:87], 1.0 op_sel_hi:[1,0]
	s_waitcnt lgkmcnt(0)
	v_pk_fma_f32 v[12:13], v[12:13], v[14:15], v[92:93]
	v_pk_fma_f32 v[14:15], v[40:41], v[86:87], v[90:91]
	ds_read_b128 v[86:89], v77 offset:6144
	ds_read_b128 v[90:93], v82 offset:14336
	ds_read_b128 v[94:97], v82 offset:6144
	v_pk_mul_f32 v[6:7], v[6:7], v[120:121] op_sel_hi:[1,0]
	v_pk_mul_f32 v[4:5], v[4:5], v[120:121] op_sel_hi:[1,0]
	ds_read_b128 v[98:101], v77 offset:7168
	s_waitcnt lgkmcnt(3)
	v_pk_mul_f32 v[40:41], v[4:5], v[86:87]
	v_pk_mul_f32 v[4:5], v[6:7], v[88:89]
	ds_read_b128 v[86:89], v82 offset:15360
	s_waitcnt lgkmcnt(3)
	v_pk_add_f32 v[6:7], v[92:93], 1.0 op_sel_hi:[1,0]
	v_pk_add_f32 v[102:103], v[90:91], 1.0 op_sel_hi:[1,0]
	ds_read_b128 v[90:93], v82 offset:7168
	v_pk_mul_f32 v[2:3], v[2:3], v[120:121] op_sel_hi:[1,0]
	v_pk_mul_f32 v[0:1], v[0:1], v[120:121] op_sel_hi:[1,0]
	s_waitcnt lgkmcnt(3)
	v_pk_fma_f32 v[4:5], v[4:5], v[6:7], v[96:97]
	v_pk_fma_f32 v[6:7], v[40:41], v[102:103], v[94:95]
	s_waitcnt lgkmcnt(2)
	v_pk_mul_f32 v[40:41], v[0:1], v[98:99]
	v_pk_mul_f32 v[0:1], v[2:3], v[100:101]
	s_waitcnt lgkmcnt(1)
	v_pk_add_f32 v[2:3], v[88:89], 1.0 op_sel_hi:[1,0]
	v_pk_add_f32 v[86:87], v[86:87], 1.0 op_sel_hi:[1,0]
	s_waitcnt lgkmcnt(0)
	v_pk_fma_f32 v[0:1], v[0:1], v[2:3], v[92:93]
	v_pk_fma_f32 v[2:3], v[40:41], v[86:87], v[90:91]
	v_cmp_lt_i32_e32 vcc, -1, v83
	s_and_saveexec_b64 s[14:15], vcc
	s_cbranch_execz .LBB0_134
	ds_read_b128 v[86:89], v78
	v_sub_f32_e32 v43, v43, v11
	v_sub_f32_e32 v42, v42, v10
	v_lshlrev_b64 v[40:41], 12, v[30:31]
	v_sub_f32_e32 v47, v47, v9
	v_sub_f32_e32 v46, v46, v8
	s_waitcnt lgkmcnt(0)
	v_pk_fma_f32 v[86:87], v[42:43], v[86:87], v[10:11]
	v_lshl_add_u64 v[40:41], v[28:29], 0, v[40:41]
	v_pk_fma_f32 v[88:89], v[46:47], v[88:89], v[8:9]
	v_cvt_pk_bf16_f32 v86, v86, v87
	v_sub_f32_e32 v45, v45, v19
	v_cvt_pk_bf16_f32 v87, v88, v89
	global_store_dwordx2 v[40:41], v[86:87], off
	ds_read_b128 v[86:89], v78 offset:1024
	v_sub_f32_e32 v44, v44, v18
	v_sub_f32_e32 v49, v49, v17
	v_sub_f32_e32 v48, v48, v16
	v_sub_f32_e32 v51, v51, v35
	s_waitcnt lgkmcnt(0)
	v_pk_fma_f32 v[86:87], v[44:45], v[86:87], v[18:19]
	v_pk_fma_f32 v[88:89], v[48:49], v[88:89], v[16:17]
	v_cvt_pk_bf16_f32 v86, v86, v87
	v_sub_f32_e32 v50, v50, v34
	v_cvt_pk_bf16_f32 v87, v88, v89
	global_store_dwordx2 v[40:41], v[86:87], off offset:512
	ds_read_b128 v[86:89], v78 offset:2048
	v_sub_f32_e32 v53, v53, v33
	v_sub_f32_e32 v52, v52, v32
	v_sub_f32_e32 v55, v55, v39
	v_sub_f32_e32 v54, v54, v38
	s_waitcnt lgkmcnt(0)
	v_pk_fma_f32 v[86:87], v[50:51], v[86:87], v[34:35]
	v_pk_fma_f32 v[88:89], v[52:53], v[88:89], v[32:33]
	v_cvt_pk_bf16_f32 v86, v86, v87
	v_sub_f32_e32 v57, v57, v37
	v_cvt_pk_bf16_f32 v87, v88, v89
	global_store_dwordx2 v[40:41], v[86:87], off offset:1024
	ds_read_b128 v[86:89], v78 offset:3072
	v_sub_f32_e32 v56, v56, v36
	v_sub_f32_e32 v59, v59, v23
	v_sub_f32_e32 v58, v58, v22
	v_sub_f32_e32 v61, v61, v21
	s_waitcnt lgkmcnt(0)
	v_pk_fma_f32 v[86:87], v[54:55], v[86:87], v[38:39]
	v_pk_fma_f32 v[88:89], v[56:57], v[88:89], v[36:37]
	v_cvt_pk_bf16_f32 v86, v86, v87
	v_sub_f32_e32 v60, v60, v20
	v_cvt_pk_bf16_f32 v87, v88, v89
	global_store_dwordx2 v[40:41], v[86:87], off offset:1536
	ds_read_b128 v[86:89], v78 offset:4096
	v_sub_f32_e32 v63, v63, v15
	v_sub_f32_e32 v62, v62, v14
	v_sub_f32_e32 v65, v65, v13
	v_sub_f32_e32 v64, v64, v12
	s_waitcnt lgkmcnt(0)
	v_pk_fma_f32 v[86:87], v[58:59], v[86:87], v[22:23]
	v_pk_fma_f32 v[88:89], v[60:61], v[88:89], v[20:21]
	v_cvt_pk_bf16_f32 v86, v86, v87
	v_sub_f32_e32 v67, v67, v7
	v_cvt_pk_bf16_f32 v87, v88, v89
	global_store_dwordx2 v[40:41], v[86:87], off offset:2048
	ds_read_b128 v[86:89], v78 offset:5120
	v_sub_f32_e32 v66, v66, v6
	v_sub_f32_e32 v69, v69, v5
	v_sub_f32_e32 v68, v68, v4
	v_sub_f32_e32 v71, v71, v3
	s_waitcnt lgkmcnt(0)
	v_pk_fma_f32 v[86:87], v[62:63], v[86:87], v[14:15]
	v_pk_fma_f32 v[88:89], v[64:65], v[88:89], v[12:13]
	v_cvt_pk_bf16_f32 v86, v86, v87
	v_sub_f32_e32 v70, v70, v2
	v_cvt_pk_bf16_f32 v87, v88, v89
	global_store_dwordx2 v[40:41], v[86:87], off offset:2560
	ds_read_b128 v[86:89], v78 offset:6144
	v_sub_f32_e32 v73, v73, v1
	v_sub_f32_e32 v72, v72, v0
	v_add_co_u32_e32 v92, vcc, s16, v40
	s_waitcnt lgkmcnt(0)
	v_pk_fma_f32 v[86:87], v[66:67], v[86:87], v[6:7]
	v_pk_fma_f32 v[88:89], v[68:69], v[88:89], v[4:5]
	v_cvt_pk_bf16_f32 v86, v86, v87
	v_addc_co_u32_e32 v93, vcc, 0, v41, vcc
	v_cvt_pk_bf16_f32 v87, v88, v89
	global_store_dwordx2 v[40:41], v[86:87], off offset:3072
	ds_read_b128 v[86:89], v78 offset:7168
	s_waitcnt lgkmcnt(0)
	v_pk_fma_f32 v[86:87], v[70:71], v[86:87], v[2:3]
	v_pk_fma_f32 v[88:89], v[72:73], v[88:89], v[0:1]
	v_cvt_pk_bf16_f32 v86, v86, v87
	s_nop 0
	v_cvt_pk_bf16_f32 v87, v88, v89
	global_store_dwordx2 v[40:41], v[86:87], off offset:3584
	ds_read_b128 v[86:89], v78 offset:8192
	s_waitcnt lgkmcnt(0)
	v_pk_fma_f32 v[88:89], v[46:47], v[88:89], v[8:9]
	v_pk_fma_f32 v[86:87], v[42:43], v[86:87], v[10:11]
	s_nop 0
	v_cvt_pk_bf16_f32 v90, v86, v87
	v_cvt_pk_bf16_f32 v91, v88, v89
	ds_read_b128 v[86:89], v78 offset:9216
	global_store_dwordx2 v[92:93], v[90:91], off
	s_waitcnt lgkmcnt(0)
	v_pk_fma_f32 v[88:89], v[48:49], v[88:89], v[16:17]
	v_pk_fma_f32 v[86:87], v[44:45], v[86:87], v[18:19]
	s_nop 0
	v_cvt_pk_bf16_f32 v90, v86, v87
	v_cvt_pk_bf16_f32 v91, v88, v89
	ds_read_b128 v[86:89], v78 offset:10240
	global_store_dwordx2 v[92:93], v[90:91], off offset:512
	s_waitcnt lgkmcnt(0)
	v_pk_fma_f32 v[88:89], v[52:53], v[88:89], v[32:33]
	v_pk_fma_f32 v[86:87], v[50:51], v[86:87], v[34:35]
	s_nop 0
	v_cvt_pk_bf16_f32 v90, v86, v87
	v_cvt_pk_bf16_f32 v91, v88, v89
	ds_read_b128 v[86:89], v78 offset:11264
	global_store_dwordx2 v[92:93], v[90:91], off offset:1024
	s_waitcnt lgkmcnt(0)
	v_pk_fma_f32 v[88:89], v[56:57], v[88:89], v[36:37]
	v_pk_fma_f32 v[86:87], v[54:55], v[86:87], v[38:39]
	s_nop 0
	v_cvt_pk_bf16_f32 v90, v86, v87
	v_cvt_pk_bf16_f32 v91, v88, v89
	ds_read_b128 v[86:89], v78 offset:12288
	global_store_dwordx2 v[92:93], v[90:91], off offset:1536
	s_waitcnt lgkmcnt(0)
	v_pk_fma_f32 v[88:89], v[60:61], v[88:89], v[20:21]
	v_pk_fma_f32 v[86:87], v[58:59], v[86:87], v[22:23]
	s_nop 0
	v_cvt_pk_bf16_f32 v90, v86, v87
	v_cvt_pk_bf16_f32 v91, v88, v89
	ds_read_b128 v[86:89], v78 offset:13312
	global_store_dwordx2 v[92:93], v[90:91], off offset:2048
	s_waitcnt lgkmcnt(0)
	v_pk_fma_f32 v[88:89], v[64:65], v[88:89], v[12:13]
	v_pk_fma_f32 v[86:87], v[62:63], v[86:87], v[14:15]
	s_nop 0
	v_cvt_pk_bf16_f32 v90, v86, v87
	v_cvt_pk_bf16_f32 v91, v88, v89
	ds_read_b128 v[86:89], v78 offset:14336
	global_store_dwordx2 v[92:93], v[90:91], off offset:2560
	s_waitcnt lgkmcnt(0)
	v_pk_fma_f32 v[88:89], v[68:69], v[88:89], v[4:5]
	v_pk_fma_f32 v[86:87], v[66:67], v[86:87], v[6:7]
	s_nop 0
	v_cvt_pk_bf16_f32 v90, v86, v87
	v_cvt_pk_bf16_f32 v91, v88, v89
	ds_read_b128 v[86:89], v78 offset:15360
	global_store_dwordx2 v[92:93], v[90:91], off offset:3072
	s_waitcnt lgkmcnt(0)
	v_pk_fma_f32 v[86:87], v[70:71], v[86:87], v[2:3]
	v_pk_fma_f32 v[88:89], v[72:73], v[88:89], v[0:1]
	v_cvt_pk_bf16_f32 v86, v86, v87
	s_nop 0
	v_cvt_pk_bf16_f32 v87, v88, v89
	global_store_dwordx2 v[92:93], v[86:87], off offset:3584
	ds_read_b128 v[86:89], v78 offset:16384
	v_add_co_u32_e32 v92, vcc, s17, v40
	s_waitcnt lgkmcnt(0)
	v_pk_fma_f32 v[88:89], v[46:47], v[88:89], v[8:9]
	v_pk_fma_f32 v[86:87], v[42:43], v[86:87], v[10:11]
	v_addc_co_u32_e32 v93, vcc, 0, v41, vcc
	v_cvt_pk_bf16_f32 v90, v86, v87
	v_cvt_pk_bf16_f32 v91, v88, v89
	ds_read_b128 v[86:89], v78 offset:17408
	global_store_dwordx2 v[92:93], v[90:91], off
	s_waitcnt lgkmcnt(0)
	v_pk_fma_f32 v[88:89], v[48:49], v[88:89], v[16:17]
	v_pk_fma_f32 v[86:87], v[44:45], v[86:87], v[18:19]
	s_nop 0
	v_cvt_pk_bf16_f32 v90, v86, v87
	v_cvt_pk_bf16_f32 v91, v88, v89
	ds_read_b128 v[86:89], v78 offset:18432
	global_store_dwordx2 v[92:93], v[90:91], off offset:512
	s_waitcnt lgkmcnt(0)
	v_pk_fma_f32 v[88:89], v[52:53], v[88:89], v[32:33]
	v_pk_fma_f32 v[86:87], v[50:51], v[86:87], v[34:35]
	s_nop 0
	v_cvt_pk_bf16_f32 v90, v86, v87
	v_cvt_pk_bf16_f32 v91, v88, v89
	ds_read_b128 v[86:89], v78 offset:19456
	global_store_dwordx2 v[92:93], v[90:91], off offset:1024
	s_waitcnt lgkmcnt(0)
	v_pk_fma_f32 v[88:89], v[56:57], v[88:89], v[36:37]
	v_pk_fma_f32 v[86:87], v[54:55], v[86:87], v[38:39]
	s_nop 0
	v_cvt_pk_bf16_f32 v90, v86, v87
	v_cvt_pk_bf16_f32 v91, v88, v89
	ds_read_b128 v[86:89], v78 offset:20480
	global_store_dwordx2 v[92:93], v[90:91], off offset:1536
	s_waitcnt lgkmcnt(0)
	v_pk_fma_f32 v[88:89], v[60:61], v[88:89], v[20:21]
	v_pk_fma_f32 v[86:87], v[58:59], v[86:87], v[22:23]
	s_nop 0
	v_cvt_pk_bf16_f32 v90, v86, v87
	v_cvt_pk_bf16_f32 v91, v88, v89
	ds_read_b128 v[86:89], v78 offset:21504
	global_store_dwordx2 v[92:93], v[90:91], off offset:2048
	s_waitcnt lgkmcnt(0)
	v_pk_fma_f32 v[88:89], v[64:65], v[88:89], v[12:13]
	v_pk_fma_f32 v[86:87], v[62:63], v[86:87], v[14:15]
	s_nop 0
	v_cvt_pk_bf16_f32 v90, v86, v87
	v_cvt_pk_bf16_f32 v91, v88, v89
	ds_read_b128 v[86:89], v78 offset:22528
	global_store_dwordx2 v[92:93], v[90:91], off offset:2560
	s_waitcnt lgkmcnt(0)
	v_pk_fma_f32 v[88:89], v[68:69], v[88:89], v[4:5]
	v_pk_fma_f32 v[86:87], v[66:67], v[86:87], v[6:7]
	s_nop 0
	v_cvt_pk_bf16_f32 v90, v86, v87
	v_cvt_pk_bf16_f32 v91, v88, v89
	ds_read_b128 v[86:89], v78 offset:23552
	global_store_dwordx2 v[92:93], v[90:91], off offset:3072
	s_waitcnt lgkmcnt(0)
	v_pk_fma_f32 v[86:87], v[70:71], v[86:87], v[2:3]
	v_pk_fma_f32 v[88:89], v[72:73], v[88:89], v[0:1]
	v_cvt_pk_bf16_f32 v86, v86, v87
	s_nop 0
	v_cvt_pk_bf16_f32 v87, v88, v89
	global_store_dwordx2 v[92:93], v[86:87], off offset:3584
	ds_read_b128 v[86:89], v78 offset:24576
	v_add_co_u32_e32 v92, vcc, s18, v40
	s_waitcnt lgkmcnt(0)
	v_pk_fma_f32 v[88:89], v[46:47], v[88:89], v[8:9]
	v_pk_fma_f32 v[86:87], v[42:43], v[86:87], v[10:11]
	v_addc_co_u32_e32 v93, vcc, 0, v41, vcc
	v_cvt_pk_bf16_f32 v90, v86, v87
	v_cvt_pk_bf16_f32 v91, v88, v89
	ds_read_b128 v[86:89], v78 offset:25600
	global_store_dwordx2 v[92:93], v[90:91], off
	s_waitcnt lgkmcnt(0)
	v_pk_fma_f32 v[88:89], v[48:49], v[88:89], v[16:17]
	v_pk_fma_f32 v[86:87], v[44:45], v[86:87], v[18:19]
	s_nop 0
	v_cvt_pk_bf16_f32 v90, v86, v87
	v_cvt_pk_bf16_f32 v91, v88, v89
	ds_read_b128 v[86:89], v78 offset:26624
	global_store_dwordx2 v[92:93], v[90:91], off offset:512
	s_waitcnt lgkmcnt(0)
	v_pk_fma_f32 v[88:89], v[52:53], v[88:89], v[32:33]
	v_pk_fma_f32 v[86:87], v[50:51], v[86:87], v[34:35]
	s_nop 0
	v_cvt_pk_bf16_f32 v90, v86, v87
	v_cvt_pk_bf16_f32 v91, v88, v89
	ds_read_b128 v[86:89], v78 offset:27648
	global_store_dwordx2 v[92:93], v[90:91], off offset:1024
	s_waitcnt lgkmcnt(0)
	v_pk_fma_f32 v[88:89], v[56:57], v[88:89], v[36:37]
	v_pk_fma_f32 v[86:87], v[54:55], v[86:87], v[38:39]
	s_nop 0
	v_cvt_pk_bf16_f32 v90, v86, v87
	v_cvt_pk_bf16_f32 v91, v88, v89
	ds_read_b128 v[86:89], v78 offset:28672
	global_store_dwordx2 v[92:93], v[90:91], off offset:1536
	s_waitcnt lgkmcnt(0)
	v_pk_fma_f32 v[88:89], v[60:61], v[88:89], v[20:21]
	v_pk_fma_f32 v[86:87], v[58:59], v[86:87], v[22:23]
	s_nop 0
	v_cvt_pk_bf16_f32 v90, v86, v87
	v_cvt_pk_bf16_f32 v91, v88, v89
	ds_read_b128 v[86:89], v78 offset:29696
	global_store_dwordx2 v[92:93], v[90:91], off offset:2048
	s_waitcnt lgkmcnt(0)
	v_pk_fma_f32 v[88:89], v[64:65], v[88:89], v[12:13]
	v_pk_fma_f32 v[86:87], v[62:63], v[86:87], v[14:15]
	s_nop 0
	v_cvt_pk_bf16_f32 v90, v86, v87
	v_cvt_pk_bf16_f32 v91, v88, v89
	ds_read_b128 v[86:89], v78 offset:30720
	global_store_dwordx2 v[92:93], v[90:91], off offset:2560
	s_waitcnt lgkmcnt(0)
	v_pk_fma_f32 v[88:89], v[68:69], v[88:89], v[4:5]
	v_pk_fma_f32 v[86:87], v[66:67], v[86:87], v[6:7]
	s_nop 0
	v_cvt_pk_bf16_f32 v90, v86, v87
	v_cvt_pk_bf16_f32 v91, v88, v89
	ds_read_b128 v[86:89], v78 offset:31744
	global_store_dwordx2 v[92:93], v[90:91], off offset:3072
	s_waitcnt lgkmcnt(0)
	v_pk_fma_f32 v[86:87], v[70:71], v[86:87], v[2:3]
	v_pk_fma_f32 v[88:89], v[72:73], v[88:89], v[0:1]
	v_cvt_pk_bf16_f32 v86, v86, v87
	s_nop 0
	v_cvt_pk_bf16_f32 v87, v88, v89
	global_store_dwordx2 v[92:93], v[86:87], off offset:3584
	ds_read_b128 v[86:89], v78 offset:32768
	v_add_co_u32_e32 v92, vcc, s19, v40
	s_waitcnt lgkmcnt(0)
	v_pk_fma_f32 v[88:89], v[46:47], v[88:89], v[8:9]
	v_pk_fma_f32 v[86:87], v[42:43], v[86:87], v[10:11]
	v_addc_co_u32_e32 v93, vcc, 0, v41, vcc
	v_cvt_pk_bf16_f32 v90, v86, v87
	v_cvt_pk_bf16_f32 v91, v88, v89
	ds_read_b128 v[86:89], v78 offset:33792
	global_store_dwordx2 v[92:93], v[90:91], off
	s_waitcnt lgkmcnt(0)
	v_pk_fma_f32 v[88:89], v[48:49], v[88:89], v[16:17]
	v_pk_fma_f32 v[86:87], v[44:45], v[86:87], v[18:19]
	s_nop 0
	v_cvt_pk_bf16_f32 v90, v86, v87
	v_cvt_pk_bf16_f32 v91, v88, v89
	ds_read_b128 v[86:89], v78 offset:34816
	global_store_dwordx2 v[92:93], v[90:91], off offset:512
	s_waitcnt lgkmcnt(0)
	v_pk_fma_f32 v[88:89], v[52:53], v[88:89], v[32:33]
	v_pk_fma_f32 v[86:87], v[50:51], v[86:87], v[34:35]
	s_nop 0
	v_cvt_pk_bf16_f32 v90, v86, v87
	v_cvt_pk_bf16_f32 v91, v88, v89
	ds_read_b128 v[86:89], v78 offset:35840
	global_store_dwordx2 v[92:93], v[90:91], off offset:1024
	s_waitcnt lgkmcnt(0)
	v_pk_fma_f32 v[88:89], v[56:57], v[88:89], v[36:37]
	v_pk_fma_f32 v[86:87], v[54:55], v[86:87], v[38:39]
	s_nop 0
	v_cvt_pk_bf16_f32 v90, v86, v87
	v_cvt_pk_bf16_f32 v91, v88, v89
	ds_read_b128 v[86:89], v78 offset:36864
	global_store_dwordx2 v[92:93], v[90:91], off offset:1536
	s_waitcnt lgkmcnt(0)
	v_pk_fma_f32 v[88:89], v[60:61], v[88:89], v[20:21]
	v_pk_fma_f32 v[86:87], v[58:59], v[86:87], v[22:23]
	s_nop 0
	v_cvt_pk_bf16_f32 v90, v86, v87
	v_cvt_pk_bf16_f32 v91, v88, v89
	ds_read_b128 v[86:89], v78 offset:37888
	global_store_dwordx2 v[92:93], v[90:91], off offset:2048
	s_waitcnt lgkmcnt(0)
	v_pk_fma_f32 v[88:89], v[64:65], v[88:89], v[12:13]
	v_pk_fma_f32 v[86:87], v[62:63], v[86:87], v[14:15]
	s_nop 0
	v_cvt_pk_bf16_f32 v90, v86, v87
	v_cvt_pk_bf16_f32 v91, v88, v89
	ds_read_b128 v[86:89], v78 offset:38912
	global_store_dwordx2 v[92:93], v[90:91], off offset:2560
	s_waitcnt lgkmcnt(0)
	v_pk_fma_f32 v[88:89], v[68:69], v[88:89], v[4:5]
	v_pk_fma_f32 v[86:87], v[66:67], v[86:87], v[6:7]
	s_nop 0
	v_cvt_pk_bf16_f32 v90, v86, v87
	v_cvt_pk_bf16_f32 v91, v88, v89
	ds_read_b128 v[86:89], v78 offset:39936
	global_store_dwordx2 v[92:93], v[90:91], off offset:3072
	s_waitcnt lgkmcnt(0)
	v_pk_fma_f32 v[86:87], v[70:71], v[86:87], v[2:3]
	v_pk_fma_f32 v[88:89], v[72:73], v[88:89], v[0:1]
	v_cvt_pk_bf16_f32 v86, v86, v87
	s_nop 0
	v_cvt_pk_bf16_f32 v87, v88, v89
	global_store_dwordx2 v[92:93], v[86:87], off offset:3584
	ds_read_b128 v[86:89], v78 offset:40960
	s_waitcnt lgkmcnt(0)
	v_pk_fma_f32 v[42:43], v[42:43], v[86:87], v[10:11]
	v_pk_fma_f32 v[46:47], v[46:47], v[88:89], v[8:9]
	v_cvt_pk_bf16_f32 v42, v42, v43
	s_nop 0
	v_cvt_pk_bf16_f32 v43, v46, v47
	ds_read_b128 v[86:89], v78 offset:41984
	v_add_co_u32_e32 v46, vcc, s20, v40
	s_nop 1
	v_addc_co_u32_e32 v47, vcc, 0, v41, vcc
	global_store_dwordx2 v[46:47], v[42:43], off
	s_waitcnt lgkmcnt(0)
	v_pk_fma_f32 v[40:41], v[48:49], v[88:89], v[16:17]
	v_pk_fma_f32 v[42:43], v[44:45], v[86:87], v[18:19]
	s_nop 0
	v_cvt_pk_bf16_f32 v44, v42, v43
	v_cvt_pk_bf16_f32 v45, v40, v41
	ds_read_b128 v[40:43], v78 offset:43008
	global_store_dwordx2 v[46:47], v[44:45], off offset:512
	s_waitcnt lgkmcnt(0)
	v_pk_fma_f32 v[42:43], v[52:53], v[42:43], v[32:33]
	v_pk_fma_f32 v[40:41], v[50:51], v[40:41], v[34:35]
	s_nop 0
	v_cvt_pk_bf16_f32 v44, v40, v41
	v_cvt_pk_bf16_f32 v45, v42, v43
	ds_read_b128 v[40:43], v78 offset:44032
	global_store_dwordx2 v[46:47], v[44:45], off offset:1024
	s_waitcnt lgkmcnt(0)
	v_pk_fma_f32 v[42:43], v[56:57], v[42:43], v[36:37]
	v_pk_fma_f32 v[40:41], v[54:55], v[40:41], v[38:39]
	s_nop 0
	v_cvt_pk_bf16_f32 v44, v40, v41
	v_cvt_pk_bf16_f32 v45, v42, v43
	ds_read_b128 v[40:43], v78 offset:45056
	global_store_dwordx2 v[46:47], v[44:45], off offset:1536
	s_waitcnt lgkmcnt(0)
	v_pk_fma_f32 v[42:43], v[60:61], v[42:43], v[20:21]
	v_pk_fma_f32 v[40:41], v[58:59], v[40:41], v[22:23]
	s_nop 0
	v_cvt_pk_bf16_f32 v44, v40, v41
	v_cvt_pk_bf16_f32 v45, v42, v43
	ds_read_b128 v[40:43], v78 offset:46080
	global_store_dwordx2 v[46:47], v[44:45], off offset:2048
	s_waitcnt lgkmcnt(0)
	v_pk_fma_f32 v[42:43], v[64:65], v[42:43], v[12:13]
	v_pk_fma_f32 v[40:41], v[62:63], v[40:41], v[14:15]
	s_nop 0
	v_cvt_pk_bf16_f32 v44, v40, v41
	v_cvt_pk_bf16_f32 v45, v42, v43
	ds_read_b128 v[40:43], v78 offset:47104
	global_store_dwordx2 v[46:47], v[44:45], off offset:2560
	s_waitcnt lgkmcnt(0)
	v_pk_fma_f32 v[42:43], v[68:69], v[42:43], v[4:5]
	v_pk_fma_f32 v[40:41], v[66:67], v[40:41], v[6:7]
	s_nop 0
	v_cvt_pk_bf16_f32 v44, v40, v41
	v_cvt_pk_bf16_f32 v45, v42, v43
	ds_read_b128 v[40:43], v78 offset:48128
	global_store_dwordx2 v[46:47], v[44:45], off offset:3072
	s_waitcnt lgkmcnt(0)
	v_pk_fma_f32 v[40:41], v[70:71], v[40:41], v[2:3]
	v_pk_fma_f32 v[42:43], v[72:73], v[42:43], v[0:1]
	v_cvt_pk_bf16_f32 v40, v40, v41
	s_nop 0
	v_cvt_pk_bf16_f32 v41, v42, v43
	global_store_dwordx2 v[46:47], v[40:41], off offset:3584
	s_and_b64 exec, exec, s[6:7]
	s_cbranch_execz .LBB0_134
	v_lshlrev_b64 v[30:31], 10, v[30:31]
	v_lshl_add_u64 v[30:31], s[4:5], 0, v[30:31]
	v_lshl_add_u64 v[30:31], v[30:31], 0, v[24:25]
	v_add_co_u32_e32 v30, vcc, 0x26000000, v30
	s_nop 1
	v_addc_co_u32_e32 v31, vcc, 0, v31, vcc
	global_store_dwordx2 v[30:31], v[84:85], off offset:896
	s_branch .LBB0_134
